# v22 + conv_group<3> (weight transposes in P4's idle workgroups) hand-rewritten with all 32 loads of an item in flight
# baseline (speedup 1.0000x reference)
.LBB0_774:
	s_abs_i32 s0, s33
	v_cvt_f32_u32_e32 v2, s0
	s_sub_i32 s1, 0, s0
	v_rcp_iflag_f32_e32 v2, v2
	s_nop 0
	v_mul_f32_e32 v2, 0x4f7ffffe, v2
	v_cvt_u32_f32_e32 v2, v2
	s_nop 0
	v_readfirstlane_b32 s2, v2
	s_mul_i32 s1, s1, s2
	s_mul_hi_u32 s1, s2, s1
	s_add_i32 s2, s2, s1
	s_mul_hi_u32 s1, s2, 0x35a
	s_mul_i32 s1, s1, s0
	s_sub_i32 s1, 0x35a, s1
	s_sub_i32 s2, s1, s0
	s_cmp_ge_u32 s1, s0
	s_cselect_b32 s1, s2, s1
	s_sub_i32 s2, s1, s0
	s_cmp_ge_u32 s1, s0
	s_cselect_b32 s0, s2, s1
	s_cmp_ge_i32 s24, s0
	s_cbranch_scc0 .LBB0_796
	s_sub_i32 s1, s24, s0
	s_lshl_b32 s1, s1, 3
	s_add_i32 s6, s1, s83
	s_cmpk_gt_u32 s6, 0x127f
	s_cbranch_scc1 .LBB0_796
	s_sub_i32 s7, s33, s0
	s_lshl_b32 s7, s7, 3
	v_mbcnt_lo_u32_b32 v1, -1, 0
	v_mbcnt_hi_u32_b32 v1, -1, v1
	v_and_b32_e32 v2, 31, v1
	v_lshrrev_b32_e32 v3, 5, v1
	s_lshl_b32 s4, s83, 14
	v_mad_u32_u24 v4, v3, 33, v2
	v_lshl_add_u32 v4, v4, 2, s4
	v_and_b32_e32 v5, 7, v1
	v_lshrrev_b32_e32 v6, 3, v1
	v_mul_u32_u24_e32 v7, 0x108, v5
	v_add_u32_e32 v7, v7, v6
	v_lshl_add_u32 v7, v7, 2, s4
.Lcv3_item:
	s_cmpk_lt_u32 s6, 2816
	s_cbranch_scc0 .Lcv3_fo
	s_mul_i32 s1, s6, 5958
	s_lshr_b32 s1, s1, 20
	s_mul_i32 s2, s1, 176
	s_sub_i32 s2, s6, s2
	s_lshl_b32 s18, s2, 5
	s_lshl_b32 s17, s1, 6
	s_cmpk_lt_u32 s18, 2816
	s_cselect_b32 s2, 0, 2816
	s_cselect_b32 s3, 0, 128
	s_sub_i32 s2, s18, s2
	s_lshr_b32 s16, s2, 7
	s_lshl_b32 s16, s16, 8
	s_and_b32 s2, s2, 127
	s_add_i32 s16, s16, s2
	s_add_i32 s16, s16, s3
	s_mov_b64 s[10:11], s[40:41]
	s_movk_i32 s12, 5632
	s_movk_i32 s13, 1024
	s_add_u32 s14, s26, 0x1400000
	s_addc_u32 s15, s27, 0
	s_branch .Lcv3_go
.Lcv3_fo:
	s_cmpk_lt_u32 s6, 4224
	s_cbranch_scc0 .Lcv3_wo
	s_sub_i32 s1, s6, 2816
	s_lshr_b32 s2, s1, 5
	s_and_b32 s1, s1, 31
	s_lshl_b32 s18, s1, 5
	s_lshl_b32 s17, s2, 6
	s_mov_b32 s16, s18
	s_mov_b64 s[10:11], s[42:43]
	s_movk_i32 s12, 1024
	s_movk_i32 s13, 2816
	s_add_u32 s14, s26, 0x2000000
	s_addc_u32 s15, s27, 0
	s_branch .Lcv3_go
.Lcv3_wo:
	s_sub_i32 s1, s6, 4224
	s_lshr_b32 s2, s1, 5
	s_and_b32 s1, s1, 31
	s_lshl_b32 s18, s1, 5
	s_lshl_b32 s17, s2, 6
	s_mov_b32 s16, s18
	s_mov_b64 s[10:11], s[46:47]
	s_movk_i32 s12, 1024
	s_movk_i32 s13, 1024
	s_add_u32 s14, s26, 0x2d00000
	s_addc_u32 s15, s27, 0
.Lcv3_go:
	s_mul_i32 s1, s17, s12
	s_add_i32 s1, s1, s18
	s_lshl_b32 s1, s1, 2
	s_add_u32 s10, s10, s1
	s_addc_u32 s11, s11, 0
	v_mul_lo_u32 v8, v3, s12
	v_add_lshl_u32 v8, v8, v2, 2
	s_lshl_b32 s19, s12, 3
	global_load_dword v16, v8, s[10:11]
	s_add_u32 s10, s10, s19
	s_addc_u32 s11, s11, 0
	global_load_dword v17, v8, s[10:11]
	s_add_u32 s10, s10, s19
	s_addc_u32 s11, s11, 0
	global_load_dword v18, v8, s[10:11]
	s_add_u32 s10, s10, s19
	s_addc_u32 s11, s11, 0
	global_load_dword v19, v8, s[10:11]
	s_add_u32 s10, s10, s19
	s_addc_u32 s11, s11, 0
	global_load_dword v20, v8, s[10:11]
	s_add_u32 s10, s10, s19
	s_addc_u32 s11, s11, 0
	global_load_dword v21, v8, s[10:11]
	s_add_u32 s10, s10, s19
	s_addc_u32 s11, s11, 0
	global_load_dword v22, v8, s[10:11]
	s_add_u32 s10, s10, s19
	s_addc_u32 s11, s11, 0
	global_load_dword v23, v8, s[10:11]
	s_add_u32 s10, s10, s19
	s_addc_u32 s11, s11, 0
	global_load_dword v24, v8, s[10:11]
	s_add_u32 s10, s10, s19
	s_addc_u32 s11, s11, 0
	global_load_dword v25, v8, s[10:11]
	s_add_u32 s10, s10, s19
	s_addc_u32 s11, s11, 0
	global_load_dword v26, v8, s[10:11]
	s_add_u32 s10, s10, s19
	s_addc_u32 s11, s11, 0
	global_load_dword v27, v8, s[10:11]
	s_add_u32 s10, s10, s19
	s_addc_u32 s11, s11, 0
	global_load_dword v28, v8, s[10:11]
	s_add_u32 s10, s10, s19
	s_addc_u32 s11, s11, 0
	global_load_dword v29, v8, s[10:11]
	s_add_u32 s10, s10, s19
	s_addc_u32 s11, s11, 0
	global_load_dword v30, v8, s[10:11]
	s_add_u32 s10, s10, s19
	s_addc_u32 s11, s11, 0
	global_load_dword v31, v8, s[10:11]
	s_add_u32 s10, s10, s19
	s_addc_u32 s11, s11, 0
	global_load_dword v32, v8, s[10:11]
	s_add_u32 s10, s10, s19
	s_addc_u32 s11, s11, 0
	global_load_dword v33, v8, s[10:11]
	s_add_u32 s10, s10, s19
	s_addc_u32 s11, s11, 0
	global_load_dword v34, v8, s[10:11]
	s_add_u32 s10, s10, s19
	s_addc_u32 s11, s11, 0
	global_load_dword v35, v8, s[10:11]
	s_add_u32 s10, s10, s19
	s_addc_u32 s11, s11, 0
	global_load_dword v36, v8, s[10:11]
	s_add_u32 s10, s10, s19
	s_addc_u32 s11, s11, 0
	global_load_dword v37, v8, s[10:11]
	s_add_u32 s10, s10, s19
	s_addc_u32 s11, s11, 0
	global_load_dword v38, v8, s[10:11]
	s_add_u32 s10, s10, s19
	s_addc_u32 s11, s11, 0
	global_load_dword v39, v8, s[10:11]
	s_add_u32 s10, s10, s19
	s_addc_u32 s11, s11, 0
	global_load_dword v40, v8, s[10:11]
	s_add_u32 s10, s10, s19
	s_addc_u32 s11, s11, 0
	global_load_dword v41, v8, s[10:11]
	s_add_u32 s10, s10, s19
	s_addc_u32 s11, s11, 0
	global_load_dword v42, v8, s[10:11]
	s_add_u32 s10, s10, s19
	s_addc_u32 s11, s11, 0
	global_load_dword v43, v8, s[10:11]
	s_add_u32 s10, s10, s19
	s_addc_u32 s11, s11, 0
	global_load_dword v44, v8, s[10:11]
	s_add_u32 s10, s10, s19
	s_addc_u32 s11, s11, 0
	global_load_dword v45, v8, s[10:11]
	s_add_u32 s10, s10, s19
	s_addc_u32 s11, s11, 0
	global_load_dword v46, v8, s[10:11]
	s_add_u32 s10, s10, s19
	s_addc_u32 s11, s11, 0
	global_load_dword v47, v8, s[10:11]
	s_mul_i32 s1, s16, s13
	s_add_i32 s1, s1, s17
	s_lshl_b32 s1, s1, 1
	s_add_u32 s14, s14, s1
	s_addc_u32 s15, s15, 0
	v_mul_lo_u32 v9, v6, s13
	v_lshl_add_u32 v80, v5, 3, v9
	v_lshlrev_b32_e32 v9, 1, v80
	s_lshl_b32 s19, s13, 4
	s_waitcnt vmcnt(31)
	ds_write_b32 v4, v16 offset:0
	s_waitcnt vmcnt(30)
	ds_write_b32 v4, v17 offset:264
	s_waitcnt vmcnt(29)
	ds_write_b32 v4, v18 offset:528
	s_waitcnt vmcnt(28)
	ds_write_b32 v4, v19 offset:792
	s_waitcnt vmcnt(27)
	ds_write_b32 v4, v20 offset:1056
	s_waitcnt vmcnt(26)
	ds_write_b32 v4, v21 offset:1320
	s_waitcnt vmcnt(25)
	ds_write_b32 v4, v22 offset:1584
	s_waitcnt vmcnt(24)
	ds_write_b32 v4, v23 offset:1848
	s_waitcnt vmcnt(23)
	ds_write_b32 v4, v24 offset:2112
	s_waitcnt vmcnt(22)
	ds_write_b32 v4, v25 offset:2376
	s_waitcnt vmcnt(21)
	ds_write_b32 v4, v26 offset:2640
	s_waitcnt vmcnt(20)
	ds_write_b32 v4, v27 offset:2904
	s_waitcnt vmcnt(19)
	ds_write_b32 v4, v28 offset:3168
	s_waitcnt vmcnt(18)
	ds_write_b32 v4, v29 offset:3432
	s_waitcnt vmcnt(17)
	ds_write_b32 v4, v30 offset:3696
	s_waitcnt vmcnt(16)
	ds_write_b32 v4, v31 offset:3960
	s_waitcnt vmcnt(15)
	ds_write_b32 v4, v32 offset:4224
	s_waitcnt vmcnt(14)
	ds_write_b32 v4, v33 offset:4488
	s_waitcnt vmcnt(13)
	ds_write_b32 v4, v34 offset:4752
	s_waitcnt vmcnt(12)
	ds_write_b32 v4, v35 offset:5016
	s_waitcnt vmcnt(11)
	ds_write_b32 v4, v36 offset:5280
	s_waitcnt vmcnt(10)
	ds_write_b32 v4, v37 offset:5544
	s_waitcnt vmcnt(9)
	ds_write_b32 v4, v38 offset:5808
	s_waitcnt vmcnt(8)
	ds_write_b32 v4, v39 offset:6072
	s_waitcnt vmcnt(7)
	ds_write_b32 v4, v40 offset:6336
	s_waitcnt vmcnt(6)
	ds_write_b32 v4, v41 offset:6600
	s_waitcnt vmcnt(5)
	ds_write_b32 v4, v42 offset:6864
	s_waitcnt vmcnt(4)
	ds_write_b32 v4, v43 offset:7128
	s_waitcnt vmcnt(3)
	ds_write_b32 v4, v44 offset:7392
	s_waitcnt vmcnt(2)
	ds_write_b32 v4, v45 offset:7656
	s_waitcnt vmcnt(1)
	ds_write_b32 v4, v46 offset:7920
	s_waitcnt vmcnt(0)
	ds_write_b32 v4, v47 offset:8184
	s_waitcnt lgkmcnt(0)
	ds_read_b32 v48, v7 offset:0
	ds_read_b32 v49, v7 offset:132
	ds_read_b32 v50, v7 offset:264
	ds_read_b32 v51, v7 offset:396
	ds_read_b32 v52, v7 offset:528
	ds_read_b32 v53, v7 offset:660
	ds_read_b32 v54, v7 offset:792
	ds_read_b32 v55, v7 offset:924
	s_waitcnt lgkmcnt(0)
	v_cvt_pk_bf16_f32 v80, v48, v49
	v_cvt_pk_bf16_f32 v81, v50, v51
	v_cvt_pk_bf16_f32 v82, v52, v53
	v_cvt_pk_bf16_f32 v83, v54, v55
	global_store_dwordx4 v9, v[80:83], s[14:15]
	s_add_u32 s14, s14, s19
	s_addc_u32 s15, s15, 0
	ds_read_b32 v56, v7 offset:32
	ds_read_b32 v57, v7 offset:164
	ds_read_b32 v58, v7 offset:296
	ds_read_b32 v59, v7 offset:428
	ds_read_b32 v60, v7 offset:560
	ds_read_b32 v61, v7 offset:692
	ds_read_b32 v62, v7 offset:824
	ds_read_b32 v63, v7 offset:956
	s_waitcnt lgkmcnt(0)
	v_cvt_pk_bf16_f32 v84, v56, v57
	v_cvt_pk_bf16_f32 v85, v58, v59
	v_cvt_pk_bf16_f32 v86, v60, v61
	v_cvt_pk_bf16_f32 v87, v62, v63
	global_store_dwordx4 v9, v[84:87], s[14:15]
	s_add_u32 s14, s14, s19
	s_addc_u32 s15, s15, 0
	ds_read_b32 v64, v7 offset:64
	ds_read_b32 v65, v7 offset:196
	ds_read_b32 v66, v7 offset:328
	ds_read_b32 v67, v7 offset:460
	ds_read_b32 v68, v7 offset:592
	ds_read_b32 v69, v7 offset:724
	ds_read_b32 v70, v7 offset:856
	ds_read_b32 v71, v7 offset:988
	s_waitcnt lgkmcnt(0)
	v_cvt_pk_bf16_f32 v88, v64, v65
	v_cvt_pk_bf16_f32 v89, v66, v67
	v_cvt_pk_bf16_f32 v90, v68, v69
	v_cvt_pk_bf16_f32 v91, v70, v71
	global_store_dwordx4 v9, v[88:91], s[14:15]
	s_add_u32 s14, s14, s19
	s_addc_u32 s15, s15, 0
	ds_read_b32 v72, v7 offset:96
	ds_read_b32 v73, v7 offset:228
	ds_read_b32 v74, v7 offset:360
	ds_read_b32 v75, v7 offset:492
	ds_read_b32 v76, v7 offset:624
	ds_read_b32 v77, v7 offset:756
	ds_read_b32 v78, v7 offset:888
	ds_read_b32 v79, v7 offset:1020
	s_waitcnt lgkmcnt(0)
	v_cvt_pk_bf16_f32 v92, v72, v73
	v_cvt_pk_bf16_f32 v93, v74, v75
	v_cvt_pk_bf16_f32 v94, v76, v77
	v_cvt_pk_bf16_f32 v95, v78, v79
	global_store_dwordx4 v9, v[92:95], s[14:15]
	s_add_i32 s6, s6, s7
	s_cmpk_lt_u32 s6, 4736
	s_cbranch_scc1 .Lcv3_item
